# v100: v96 + seam tail hand-written: XCD last arriver bumps one counter per XCC (fire-and-forget), every WG polls its own XCC counter; no TOP round trip, no per-XCC generation hop
# speedup vs baseline: 1.0104x; 1.0040x over previous
.LBB0_138:
	s_or_b64 exec, exec, s[16:17]
	v_cvt_f32_u32_e32 v4, v2
	s_waitcnt vmcnt(0)
	v_readfirstlane_b32 s3, v3
	v_sub_u32_e32 v3, 0, v2
	v_rcp_iflag_f32_e32 v4, v4
	v_add_u32_e32 v5, s3, v1
	v_mul_f32_e32 v4, 0x4f7ffffe, v4
	v_cvt_u32_f32_e32 v4, v4
	v_mul_lo_u32 v1, v3, v4
	v_mul_hi_u32 v1, v4, v1
	v_add_u32_e32 v1, v4, v1
	v_mul_hi_u32 v1, v5, v1
	v_mul_lo_u32 v3, v1, v2
	v_sub_u32_e32 v3, v5, v3
	v_add_u32_e32 v4, 1, v1
	v_cmp_ge_u32_e32 vcc, v3, v2
	s_nop 1
	v_cndmask_b32_e32 v1, v1, v4, vcc
	v_sub_u32_e32 v4, v3, v2
	v_cndmask_b32_e32 v3, v3, v4, vcc
	v_add_u32_e32 v4, 1, v1
	v_cmp_ge_u32_e32 vcc, v3, v2
	v_add_u32_e32 v3, 1, v5
	s_nop 0
	v_cndmask_b32_e32 v1, v1, v4, vcc
	v_mul_lo_u32 v4, v2, v1
	v_add_u32_e32 v2, v4, v2
	v_cmp_ne_u32_e32 vcc, v3, v2
	s_waitcnt lgkmcnt(0)
	v_mul_lo_u32 v4, v1, v0
	v_add_u32_e32 v4, v4, v0
	v_mov_b32_e32 v5, 0x2480
	s_cbranch_vccnz .Lsb_poll0
	buffer_wbl2 sc1
	s_waitcnt vmcnt(0)
	s_add_u32 s16, s10, 0x62480
	s_addc_u32 s17, s11, 0
	v_mov_b32_e32 v6, 0
	v_mov_b32_e32 v7, 1
	global_atomic_add v6, v7, s[16:17]
	global_atomic_add v6, v7, s[16:17] offset:256
	global_atomic_add v6, v7, s[16:17] offset:512
	global_atomic_add v6, v7, s[16:17] offset:768
	global_atomic_add v6, v7, s[16:17] offset:1024
	global_atomic_add v6, v7, s[16:17] offset:1280
	global_atomic_add v6, v7, s[16:17] offset:1536
	global_atomic_add v6, v7, s[16:17] offset:1792
	global_atomic_add v6, v7, s[16:17] offset:2048
	global_atomic_add v6, v7, s[16:17] offset:2304
	global_atomic_add v6, v7, s[16:17] offset:2560
	global_atomic_add v6, v7, s[16:17] offset:2816
	global_atomic_add v6, v7, s[16:17] offset:3072
	global_atomic_add v6, v7, s[16:17] offset:3328
	global_atomic_add v6, v7, s[16:17] offset:3584
	global_atomic_add v6, v7, s[16:17] offset:3840
.Lsb_poll0:
	s_mov_b32 s3, 0
.Lsb_loop0:
	global_load_dword v3, v5, s[12:13] sc1
	s_waitcnt vmcnt(0)
	v_cmp_ge_u32_e32 vcc, v3, v4
	s_cbranch_vccnz .Lsb_done0
	s_sleep 1
	s_add_i32 s3, s3, 1
	s_cmp_lt_u32 s3, 0x100000
	s_cbranch_scc1 .Lsb_loop0
.Lsb_done0:
	buffer_inv sc1
	s_waitcnt vmcnt(0)

.LBB0_430:
	s_or_b64 exec, exec, s[14:15]
	v_cvt_f32_u32_e32 v4, v2
	s_waitcnt vmcnt(0)
	v_readfirstlane_b32 s3, v3
	v_sub_u32_e32 v3, 0, v2
	v_rcp_iflag_f32_e32 v4, v4
	v_add_u32_e32 v5, s3, v1
	v_mul_f32_e32 v4, 0x4f7ffffe, v4
	v_cvt_u32_f32_e32 v4, v4
	v_mul_lo_u32 v1, v3, v4
	v_mul_hi_u32 v1, v4, v1
	v_add_u32_e32 v1, v4, v1
	v_mul_hi_u32 v1, v5, v1
	v_mul_lo_u32 v3, v1, v2
	v_sub_u32_e32 v3, v5, v3
	v_add_u32_e32 v4, 1, v1
	v_cmp_ge_u32_e32 vcc, v3, v2
	s_nop 1
	v_cndmask_b32_e32 v1, v1, v4, vcc
	v_sub_u32_e32 v4, v3, v2
	v_cndmask_b32_e32 v3, v3, v4, vcc
	v_add_u32_e32 v4, 1, v1
	v_cmp_ge_u32_e32 vcc, v3, v2
	v_add_u32_e32 v3, 1, v5
	s_nop 0
	v_cndmask_b32_e32 v1, v1, v4, vcc
	v_mul_lo_u32 v4, v2, v1
	v_add_u32_e32 v2, v4, v2
	v_cmp_ne_u32_e32 vcc, v3, v2
	s_waitcnt lgkmcnt(0)
	v_mul_lo_u32 v4, v1, v0
	v_add_u32_e32 v4, v4, v0
	v_mov_b32_e32 v5, 0x2480
	s_cbranch_vccnz .Lsb_poll4
	buffer_wbl2 sc1
	s_waitcnt vmcnt(0)
	s_add_u32 s16, s4, 0x62480
	s_addc_u32 s17, s5, 0
	v_mov_b32_e32 v6, 0
	v_mov_b32_e32 v7, 1
	global_atomic_add v6, v7, s[16:17]
	global_atomic_add v6, v7, s[16:17] offset:256
	global_atomic_add v6, v7, s[16:17] offset:512
	global_atomic_add v6, v7, s[16:17] offset:768
	global_atomic_add v6, v7, s[16:17] offset:1024
	global_atomic_add v6, v7, s[16:17] offset:1280
	global_atomic_add v6, v7, s[16:17] offset:1536
	global_atomic_add v6, v7, s[16:17] offset:1792
	global_atomic_add v6, v7, s[16:17] offset:2048
	global_atomic_add v6, v7, s[16:17] offset:2304
	global_atomic_add v6, v7, s[16:17] offset:2560
	global_atomic_add v6, v7, s[16:17] offset:2816
	global_atomic_add v6, v7, s[16:17] offset:3072
	global_atomic_add v6, v7, s[16:17] offset:3328
	global_atomic_add v6, v7, s[16:17] offset:3584
	global_atomic_add v6, v7, s[16:17] offset:3840

.Lsb_loop4:
	global_load_dword v3, v5, s[10:11] sc1
	s_waitcnt vmcnt(0)
	v_cmp_ge_u32_e32 vcc, v3, v4
	s_cbranch_vccnz .Lsb_done4
	s_sleep 1
	s_add_i32 s3, s3, 1
	s_cmp_lt_u32 s3, 0x100000
	s_cbranch_scc1 .Lsb_loop4
